# seam 4 also team-local with a wait on the previous panel's team (pool history rows); one global same-XCD flag from all 64 teams' XCC ids; only seam 0 remains a grid barrier
# speedup vs baseline: 1.0558x; 1.0148x over previous
; #define LAS __attribute__((address_space(3)))
; __device__ __forceinline__ unsigned xb_ld(unsigned* p)              { return __hip_atomic_load(p, __ATOMIC_RELAXED, __HIP_MEMORY_SCOPE_AGENT); }
; __device__ __forceinline__ unsigned xb_add(unsigned* p, unsigned v) { return __hip_atomic_fetch_add(p, v, __ATOMIC_RELAXED, __HIP_MEMORY_SCOPE_AGENT); }
; __device__ __forceinline__ unsigned xb_xcc_id() { return (unsigned)__builtin_amdgcn_s_getreg((3 << 11) | 20) & 0xFu; }
; __device__ __forceinline__ XcdBarrier xcd_barrier_post(unsigned* bar, volatile LAS unsigned* st) {
;     XcdBarrier b; b.bar = bar; b.x = xb_xcc_id(); b.st = st;
;     if (threadIdx.x == 0) (void)xb_add(&bar[XB_XCNT(b.x)], 1u);
;     return b;
; }
; __device__ __forceinline__ void xcd_barrier_complete(unsigned* bar, unsigned x, unsigned& nloc, unsigned& nx) {
;     const unsigned G = gridDim.x * gridDim.y * gridDim.z;
;     unsigned sum, cnt, mine, sp = 0u;
;     for (;;) {
;         sum = 0u; cnt = 0u; mine = 0u;
; #pragma unroll
;         for (unsigned j = 0; j < 16; ++j) { const unsigned c = xb_ld(&bar[XB_XCNT(j)]); sum += c; cnt += (c > 0u) ? 1u : 0u; mine = (j == x) ? c : mine; }
;         if (sum == G) break;
;         __builtin_amdgcn_s_sleep(1);
;         if ((++sp & 255u) == 0u) { if (xb_ld(&bar[XB_TMO])) break; if (sp > XB_SPIN_CAP) { atomicAdd(&bar[XB_TMO], 1u); break; } }
;     }
;     nloc = mine > 0u ? mine : 1u; nx = cnt > 0u ? cnt : 1u;
; }
; __global__ void __launch_bounds__(NWAVES * 64, 2) mk_fwd(Args a) {
;     ...
;     if (IN(1)) { pg8::Gemm g{XN, WGU1, M, 2 * FF, D}; pg8::StaticOrder S; S.init(M, 2 * FF, G, bid); EpiGU E{ACT, RS, lds}; rs_table_fill(lds, S, RS);
.LBB0_212:
	s_add_u32 s4, s28, 0x3903600
	s_addc_u32 s5, s29, 0
	v_and_b32_e32 v0, 63, v195
	v_lshlrev_b32_e32 v0, 5, v0
	global_load_dwordx4 v[0:3], v0, s[4:5] offset:16 sc1
	s_waitcnt vmcnt(0)
	v_min_u32_e32 v4, v0, v1
	v_max_u32_e32 v5, v0, v1
	v_min3_u32 v4, v4, v2, v3
	v_max3_u32 v5, v5, v2, v3
	s_nop 1
	v_min_u32_dpp v4, v4, v4 quad_perm:[1,0,3,2] row_mask:0xf bank_mask:0xf
	v_max_u32_dpp v5, v5, v5 quad_perm:[1,0,3,2] row_mask:0xf bank_mask:0xf
	s_nop 1
	v_min_u32_dpp v4, v4, v4 quad_perm:[2,3,0,1] row_mask:0xf bank_mask:0xf
	v_max_u32_dpp v5, v5, v5 quad_perm:[2,3,0,1] row_mask:0xf bank_mask:0xf
	s_nop 1
	v_min_u32_dpp v4, v4, v4 row_half_mirror row_mask:0xf bank_mask:0xf
	v_max_u32_dpp v5, v5, v5 row_half_mirror row_mask:0xf bank_mask:0xf
	s_nop 1
	v_cmp_eq_u32_e32 vcc, v4, v5
	s_mov_b64 s[4:5], vcc
	v_cmp_ne_u32_e32 vcc, 0, v4
	s_and_b64 s[4:5], s[4:5], vcc
	s_cmp_eq_u64 s[4:5], exec
	s_cselect_b32 s99, 1, 0
	s_cmp_lt_i32 s30, 2
	s_cselect_b64 s[4:5], -1, 0
	s_add_u32 s16, s28, 0x9000000
	s_addc_u32 s17, s29, 0
	s_and_b64 s[12:13], s[4:5], s[0:1]
	s_andn2_b64 vcc, exec, s[12:13]
	s_cbranch_vccnz .LBB0_257
	s_mov_b32 s14, -1
	s_ashr_i32 s3, s2, 31
	s_mov_b32 s15, s14
	s_ashr_i32 s8, s33, 31
	s_waitcnt vmcnt(15)
	v_mov_b64_e32 v[0:1], 0xb00
	v_mov_b64_e32 v[2:3], 0xaff
	s_movk_i32 s24, 0x161
	s_mov_b64 s[20:21], s[2:3]
	s_mov_b32 s9, s14
	s_mov_b64 s[18:19], s[14:15]
	s_branch .LBB0_216

; __device__ __forceinline__ unsigned xb_ld(unsigned* p)              { return __hip_atomic_load(p, __ATOMIC_RELAXED, __HIP_MEMORY_SCOPE_AGENT); }
; #define XB_SPIN(cond, bar) do { unsigned _sp = 0; while (cond) { __builtin_amdgcn_s_sleep(1); \
;     if ((++_sp & 255u) == 0u) { if (xb_ld(&(bar)[XB_TMO])) break; if (_sp > XB_SPIN_CAP) { atomicAdd(&(bar)[XB_TMO], 1u); break; } } } } while (0)
; __device__ __forceinline__ void xcd_barrier(const XcdBarrier& b) {
;     ...
;             XB_SPIN(xb_ld(&bar[XB_XGEN(b.x)]) == gen, bar);
.Ltb307_sspin:
	global_load_dword v3, v0, s[8:9] sc1
	s_waitcnt vmcnt(0)
	v_cmp_ge_u32_e32 vcc, v3, v2
	s_cbranch_vccnz .Ltb307_srel
	s_sleep 1
	s_add_u32 s15, s15, 1
	s_cmp_lt_u32 s15, 0x400000
	s_cbranch_scc1 .Ltb307_sspin

; __device__ __forceinline__ void xcd_barrier(const XcdBarrier& b) {
;     ...
;     }
;     __syncthreads();
.Ltb307_frel:
.Ltb307_done:
	s_or_b64 exec, exec, s[4:5]
	s_barrier

; __device__ __forceinline__ unsigned xb_add(unsigned* p, unsigned v) { return __hip_atomic_fetch_add(p, v, __ATOMIC_RELAXED, __HIP_MEMORY_SCOPE_AGENT); }
; #define SEAM(k) do { if (IN(k) && IN((k) + 1)) { xcd_barrier(xbar); } } while (0)
; __device__ __forceinline__ void xcd_barrier(const XcdBarrier& b) {
;     asm volatile("s_waitcnt vmcnt(0)" ::: "memory");
;     __syncthreads();
;     if (threadIdx.x == 0) {
;         unsigned* bar = b.bar;
;         __builtin_amdgcn_s_waitcnt(0);
;         unsigned nloc = b.st[0], nx = b.st[1];
;         if (nloc == 0u) { xcd_barrier_complete(bar, b.x, nloc, nx); b.st[0] = nloc; b.st[1] = nx; }
;         const unsigned old = xb_add(&bar[XB_XSUB(b.x)], 1u);
;         const unsigned gen = old / nloc;
;         if (old + 1u == (gen + 1u) * nloc) {
;             __builtin_amdgcn_fence(__ATOMIC_RELEASE, "agent");
;             asm volatile("s_waitcnt vmcnt(0)" ::: "memory");
;             const unsigned og = xb_add(&bar[XB_TOP], 1u);
; __global__ void __launch_bounds__(NWAVES * 64, 2) mk_fwd(Args a) {
;     ...
;     SEAM(4);
.LBB0_625:
	s_cmp_gt_i32 s31, 5
	s_cselect_b64 s[0:1], -1, 0
	s_and_b64 s[4:5], s[12:13], s[0:1]
	s_andn2_b64 vcc, exec, s[4:5]
	s_cbranch_vccnz .LBB0_675
	s_waitcnt vmcnt(0)
	s_barrier
	v_cmp_eq_u32_e32 vcc, 0, v195
	s_and_saveexec_b64 s[4:5], vcc
	s_cbranch_execz .Ltb675_done
	s_and_b32 s3, s2, 7
	s_lshl_b32 s3, s3, 3
	s_bfe_u32 s13, s2, 0x30003
	s_or_b32 s3, s3, s13
	s_lshl_b32 s3, s3, 5
	s_add_u32 s8, s28, 0x3903600
	s_addc_u32 s9, s29, 0
	v_mov_b32_e32 v0, s3
	v_mov_b32_e32 v1, 1
	v_mov_b32_e32 v2, 16
	s_mov_b32 s15, 0
	s_cmp_eq_u32 s99, 1
	s_cbranch_scc1 .Ltb675_fast
	buffer_wbl2 sc1
	s_waitcnt vmcnt(0)
	global_atomic_add v0, v1, s[8:9]

; __device__ __forceinline__ unsigned xb_ld(unsigned* p)              { return __hip_atomic_load(p, __ATOMIC_RELAXED, __HIP_MEMORY_SCOPE_AGENT); }
; #define XB_SPIN(cond, bar) do { unsigned _sp = 0; while (cond) { __builtin_amdgcn_s_sleep(1); \
;     if ((++_sp & 255u) == 0u) { if (xb_ld(&(bar)[XB_TMO])) break; if (_sp > XB_SPIN_CAP) { atomicAdd(&(bar)[XB_TMO], 1u); break; } } } } while (0)
; __device__ __forceinline__ void mixer_phase(LAS unsigned char* lds, bf16* U  , const bf16* V, const bf16* C, bf16* Bout,
;                                             const bf16* wsb, const float* sgu_b, const float* sgu_g, const bf16* pwT, const float* pool_scale, int G, int bid) {
;     ...
;                 const bool has_hist = (q & 31) != 0;
;                 v4u cv[9];
; #pragma unroll
;                 for (int i = 0; i < 9; ++i) { const int id = tid + 512 * i, row = id >> 5, c8 = id & 31;
;                     cv[i] = (v4u){0u, 0u, 0u, 0u};
;                     if (id < 143 * 32 && (row >= 15 || has_hist)) cv[i] = *(const v4u*)(C + ((ptrdiff_t)r0 + row - 15) * D + gi * 256 + c8 * 8); }
; __device__ __forceinline__ void xcd_barrier(const XcdBarrier& b) {
;     ...
;             asm volatile("s_waitcnt vmcnt(0)" ::: "memory");
;         } else {
;             XB_SPIN(xb_ld(&bar[XB_XGEN(b.x)]) == gen, bar);
;             __builtin_amdgcn_fence(__ATOMIC_ACQUIRE, "agent");
;             asm volatile("s_waitcnt vmcnt(0)" ::: "memory");
.Ltb675_srel:
	s_bitcmp1_b32 s2, 6
	s_cbranch_scc1 .Ltb675_snbd
	s_cmp_lt_u32 s2, 8
	s_cbranch_scc1 .Ltb675_snbd
	s_bfe_u32 s13, s2, 0x30003
	s_add_u32 s13, s13, 7
	s_and_b32 s13, s13, 7
	s_and_b32 s3, s2, 7
	s_lshl_b32 s3, s3, 3
	s_or_b32 s3, s3, s13
	s_lshl_b32 s3, s3, 5
	v_mov_b32_e32 v0, s3

; __device__ __forceinline__ unsigned xb_add(unsigned* p, unsigned v) { return __hip_atomic_fetch_add(p, v, __ATOMIC_RELAXED, __HIP_MEMORY_SCOPE_AGENT); }
; #define SEAM(k) do { if (IN(k) && IN((k) + 1)) { xcd_barrier(xbar); } } while (0)
; __device__ __forceinline__ void xcd_barrier(const XcdBarrier& b) {
;     asm volatile("s_waitcnt vmcnt(0)" ::: "memory");
;     __syncthreads();
;     if (threadIdx.x == 0) {
;         unsigned* bar = b.bar;
;         __builtin_amdgcn_s_waitcnt(0);
;         unsigned nloc = b.st[0], nx = b.st[1];
;         if (nloc == 0u) { xcd_barrier_complete(bar, b.x, nloc, nx); b.st[0] = nloc; b.st[1] = nx; }
;         const unsigned old = xb_add(&bar[XB_XSUB(b.x)], 1u);
;         const unsigned gen = old / nloc;
;         if (old + 1u == (gen + 1u) * nloc) {
;             __builtin_amdgcn_fence(__ATOMIC_RELEASE, "agent");
;             asm volatile("s_waitcnt vmcnt(0)" ::: "memory");
;             const unsigned og = xb_add(&bar[XB_TOP], 1u);
; __global__ void __launch_bounds__(NWAVES * 64, 2) mk_fwd(Args a) {
;     ...
;     SEAM(5);
.LBB0_719:
	s_mov_b32 s2, s98
	s_cmp_gt_i32 s31, 6
	s_cselect_b64 s[0:1], -1, 0
	s_and_b64 s[4:5], s[14:15], s[0:1]
	s_andn2_b64 vcc, exec, s[4:5]
	s_cbranch_vccnz .LBB0_769
	s_waitcnt vmcnt(0)
	s_barrier
	v_cmp_eq_u32_e32 vcc, 0, v195
	s_and_saveexec_b64 s[4:5], vcc
	s_cbranch_execz .Ltb769_done
	s_and_b32 s3, s2, 7
	s_lshl_b32 s3, s3, 3
	s_bfe_u32 s13, s2, 0x30003
	s_or_b32 s3, s3, s13
	s_lshl_b32 s3, s3, 5
	s_add_u32 s8, s28, 0x3903600
	s_addc_u32 s9, s29, 0
	v_mov_b32_e32 v0, s3
	v_mov_b32_e32 v1, 1
	v_mov_b32_e32 v2, 20
	s_mov_b32 s15, 0
	s_cmp_eq_u32 s99, 1
	s_cbranch_scc1 .Ltb769_fast
	buffer_wbl2 sc1
	s_waitcnt vmcnt(0)
	global_atomic_add v0, v1, s[8:9]

; __device__ __forceinline__ unsigned xb_add(unsigned* p, unsigned v) { return __hip_atomic_fetch_add(p, v, __ATOMIC_RELAXED, __HIP_MEMORY_SCOPE_AGENT); }
; #define SEAM(k) do { if (IN(k) && IN((k) + 1)) { xcd_barrier(xbar); } } while (0)
; __device__ __forceinline__ void xcd_barrier(const XcdBarrier& b) {
;     asm volatile("s_waitcnt vmcnt(0)" ::: "memory");
;     __syncthreads();
;     if (threadIdx.x == 0) {
;         unsigned* bar = b.bar;
;         __builtin_amdgcn_s_waitcnt(0);
;         unsigned nloc = b.st[0], nx = b.st[1];
;         if (nloc == 0u) { xcd_barrier_complete(bar, b.x, nloc, nx); b.st[0] = nloc; b.st[1] = nx; }
;         const unsigned old = xb_add(&bar[XB_XSUB(b.x)], 1u);
;         const unsigned gen = old / nloc;
;         if (old + 1u == (gen + 1u) * nloc) {
;             __builtin_amdgcn_fence(__ATOMIC_RELEASE, "agent");
;             asm volatile("s_waitcnt vmcnt(0)" ::: "memory");
;             const unsigned og = xb_add(&bar[XB_TOP], 1u);
; __global__ void __launch_bounds__(NWAVES * 64, 2) mk_fwd(Args a) {
;     ...
;     SEAM(6);
.LBB0_818:
	s_cmp_gt_i32 s31, 7
	s_cselect_b64 s[0:1], -1, 0
	s_and_b64 s[4:5], s[4:5], s[0:1]
	v_readlane_b32 s68, v254, 8
	v_readlane_b32 s70, v254, 6
	v_readlane_b32 s76, v254, 4
	s_andn2_b64 vcc, exec, s[4:5]
	v_readlane_b32 s69, v254, 9
	v_readlane_b32 s71, v254, 7
	v_readlane_b32 s77, v254, 5
	s_cbranch_vccnz .LBB0_868
	s_waitcnt vmcnt(0)
	s_barrier
	v_cmp_eq_u32_e32 vcc, 0, v195
	s_and_saveexec_b64 s[4:5], vcc
	s_cbranch_execz .Ltb868_done
	s_and_b32 s3, s2, 7
	s_lshl_b32 s3, s3, 3
	s_bfe_u32 s13, s2, 0x30003
	s_or_b32 s3, s3, s13
	s_lshl_b32 s3, s3, 5
	s_add_u32 s8, s28, 0x3903600
	s_addc_u32 s9, s29, 0
	v_mov_b32_e32 v0, s3
	v_mov_b32_e32 v1, 1
	v_mov_b32_e32 v2, 24
	s_mov_b32 s15, 0
	s_cmp_eq_u32 s99, 1
	s_cbranch_scc1 .Ltb868_fast
	buffer_wbl2 sc1
	s_waitcnt vmcnt(0)
	global_atomic_add v0, v1, s[8:9]

; __device__ __forceinline__ unsigned xb_add(unsigned* p, unsigned v) { return __hip_atomic_fetch_add(p, v, __ATOMIC_RELAXED, __HIP_MEMORY_SCOPE_AGENT); }
; #define SEAM(k) do { if (IN(k) && IN((k) + 1)) { xcd_barrier(xbar); } } while (0)
; __device__ __forceinline__ void xcd_barrier(const XcdBarrier& b) {
;     asm volatile("s_waitcnt vmcnt(0)" ::: "memory");
;     __syncthreads();
;     if (threadIdx.x == 0) {
;         unsigned* bar = b.bar;
;         __builtin_amdgcn_s_waitcnt(0);
;         unsigned nloc = b.st[0], nx = b.st[1];
;         if (nloc == 0u) { xcd_barrier_complete(bar, b.x, nloc, nx); b.st[0] = nloc; b.st[1] = nx; }
;         const unsigned old = xb_add(&bar[XB_XSUB(b.x)], 1u);
;         const unsigned gen = old / nloc;
;         if (old + 1u == (gen + 1u) * nloc) {
;             __builtin_amdgcn_fence(__ATOMIC_RELEASE, "agent");
;             asm volatile("s_waitcnt vmcnt(0)" ::: "memory");
;             const unsigned og = xb_add(&bar[XB_TOP], 1u);
; __global__ void __launch_bounds__(NWAVES * 64, 2) mk_fwd(Args a) {
;     ...
;     SEAM(7);
.LBB0_893:
	s_cmp_gt_i32 s31, 8
	s_cselect_b64 s[0:1], -1, 0
	s_and_b64 s[4:5], s[4:5], s[0:1]
	s_andn2_b64 vcc, exec, s[4:5]
	s_cbranch_vccnz .LBB0_943
	s_waitcnt vmcnt(0)
	s_barrier
	v_cmp_eq_u32_e32 vcc, 0, v195
	s_and_saveexec_b64 s[4:5], vcc
	s_cbranch_execz .Ltb943_done
	s_and_b32 s3, s2, 7
	s_lshl_b32 s3, s3, 3
	s_bfe_u32 s13, s2, 0x30003
	s_or_b32 s3, s3, s13
	s_lshl_b32 s3, s3, 5
	s_add_u32 s8, s28, 0x3903600
	s_addc_u32 s9, s29, 0
	v_mov_b32_e32 v0, s3
	v_mov_b32_e32 v1, 1
	v_mov_b32_e32 v2, 28
	s_mov_b32 s15, 0
	s_cmp_eq_u32 s99, 1
	s_cbranch_scc1 .Ltb943_fast
	buffer_wbl2 sc1
	s_waitcnt vmcnt(0)
	global_atomic_add v0, v1, s[8:9]

; __device__ __forceinline__ unsigned xb_add(unsigned* p, unsigned v) { return __hip_atomic_fetch_add(p, v, __ATOMIC_RELAXED, __HIP_MEMORY_SCOPE_AGENT); }
; #define SEAM(k) do { if (IN(k) && IN((k) + 1)) { xcd_barrier(xbar); } } while (0)
; __device__ __forceinline__ void xcd_barrier(const XcdBarrier& b) {
;     asm volatile("s_waitcnt vmcnt(0)" ::: "memory");
;     __syncthreads();
;     if (threadIdx.x == 0) {
;         unsigned* bar = b.bar;
;         __builtin_amdgcn_s_waitcnt(0);
;         unsigned nloc = b.st[0], nx = b.st[1];
;         if (nloc == 0u) { xcd_barrier_complete(bar, b.x, nloc, nx); b.st[0] = nloc; b.st[1] = nx; }
;         const unsigned old = xb_add(&bar[XB_XSUB(b.x)], 1u);
;         const unsigned gen = old / nloc;
;         if (old + 1u == (gen + 1u) * nloc) {
;             __builtin_amdgcn_fence(__ATOMIC_RELEASE, "agent");
;             asm volatile("s_waitcnt vmcnt(0)" ::: "memory");
;             const unsigned og = xb_add(&bar[XB_TOP], 1u);
; __global__ void __launch_bounds__(NWAVES * 64, 2) mk_fwd(Args a) {
;     ...
;     SEAM(8);
.LBB0_989:
	s_cmp_gt_i32 s31, 9
	s_cselect_b64 s[0:1], -1, 0
	s_and_b64 s[4:5], s[8:9], s[0:1]
	s_andn2_b64 vcc, exec, s[4:5]
	s_cbranch_vccnz .LBB0_1039
	s_waitcnt vmcnt(0)
	s_barrier
	v_cmp_eq_u32_e32 vcc, 0, v195
	s_and_saveexec_b64 s[4:5], vcc
	s_cbranch_execz .Ltb1039_done
	s_and_b32 s3, s2, 7
	s_lshl_b32 s3, s3, 3
	s_bfe_u32 s13, s2, 0x30003
	s_or_b32 s3, s3, s13
	s_lshl_b32 s3, s3, 5
	s_add_u32 s8, s28, 0x3903600
	s_addc_u32 s9, s29, 0
	v_mov_b32_e32 v0, s3
	v_mov_b32_e32 v1, 1
	v_mov_b32_e32 v2, 32
	s_mov_b32 s15, 0
	s_cmp_eq_u32 s99, 1
	s_cbranch_scc1 .Ltb1039_fast
	buffer_wbl2 sc1
	s_waitcnt vmcnt(0)
	global_atomic_add v0, v1, s[8:9]

; __device__ __forceinline__ unsigned xb_add(unsigned* p, unsigned v) { return __hip_atomic_fetch_add(p, v, __ATOMIC_RELAXED, __HIP_MEMORY_SCOPE_AGENT); }
; #define SEAM(k) do { if (IN(k) && IN((k) + 1)) { xcd_barrier(xbar); } } while (0)
; __device__ __forceinline__ void xcd_barrier(const XcdBarrier& b) {
;     asm volatile("s_waitcnt vmcnt(0)" ::: "memory");
;     __syncthreads();
;     if (threadIdx.x == 0) {
;         unsigned* bar = b.bar;
;         __builtin_amdgcn_s_waitcnt(0);
;         unsigned nloc = b.st[0], nx = b.st[1];
;         if (nloc == 0u) { xcd_barrier_complete(bar, b.x, nloc, nx); b.st[0] = nloc; b.st[1] = nx; }
;         const unsigned old = xb_add(&bar[XB_XSUB(b.x)], 1u);
;         const unsigned gen = old / nloc;
;         if (old + 1u == (gen + 1u) * nloc) {
;             __builtin_amdgcn_fence(__ATOMIC_RELEASE, "agent");
;             asm volatile("s_waitcnt vmcnt(0)" ::: "memory");
;             const unsigned og = xb_add(&bar[XB_TOP], 1u);
; __global__ void __launch_bounds__(NWAVES * 64, 2) mk_fwd(Args a) {
;     ...
;     SEAM(9);
.LBB0_1084:
	s_cmp_gt_i32 s31, 10
	s_cselect_b64 s[0:1], -1, 0
	s_and_b64 s[4:5], s[6:7], s[0:1]
	s_andn2_b64 vcc, exec, s[4:5]
	s_cbranch_vccnz .LBB0_1134
	s_waitcnt vmcnt(0)
	s_barrier
	v_cmp_eq_u32_e32 vcc, 0, v195
	s_and_saveexec_b64 s[4:5], vcc
	s_cbranch_execz .Ltb1134_done
	s_and_b32 s3, s2, 7
	s_lshl_b32 s3, s3, 3
	s_bfe_u32 s13, s2, 0x30003
	s_or_b32 s3, s3, s13
	s_lshl_b32 s3, s3, 5
	s_add_u32 s8, s28, 0x3903600
	s_addc_u32 s9, s29, 0
	v_mov_b32_e32 v0, s3
	v_mov_b32_e32 v1, 1
	v_mov_b32_e32 v2, 36
	s_mov_b32 s15, 0
	s_cmp_eq_u32 s99, 1
	s_cbranch_scc1 .Ltb1134_fast
	buffer_wbl2 sc1
	s_waitcnt vmcnt(0)
	global_atomic_add v0, v1, s[8:9]

; __device__ __forceinline__ unsigned xb_add(unsigned* p, unsigned v) { return __hip_atomic_fetch_add(p, v, __ATOMIC_RELAXED, __HIP_MEMORY_SCOPE_AGENT); }
; #define SEAM(k) do { if (IN(k) && IN((k) + 1)) { xcd_barrier(xbar); } } while (0)
; __device__ __forceinline__ void xcd_barrier(const XcdBarrier& b) {
;     asm volatile("s_waitcnt vmcnt(0)" ::: "memory");
;     __syncthreads();
;     if (threadIdx.x == 0) {
;         unsigned* bar = b.bar;
;         __builtin_amdgcn_s_waitcnt(0);
;         unsigned nloc = b.st[0], nx = b.st[1];
;         if (nloc == 0u) { xcd_barrier_complete(bar, b.x, nloc, nx); b.st[0] = nloc; b.st[1] = nx; }
;         const unsigned old = xb_add(&bar[XB_XSUB(b.x)], 1u);
;         const unsigned gen = old / nloc;
;         if (old + 1u == (gen + 1u) * nloc) {
;             __builtin_amdgcn_fence(__ATOMIC_RELEASE, "agent");
;             asm volatile("s_waitcnt vmcnt(0)" ::: "memory");
;             const unsigned og = xb_add(&bar[XB_TOP], 1u);
; __global__ void __launch_bounds__(NWAVES * 64, 2) mk_fwd(Args a) {
;     ...
;     SEAM(10);
.LBB0_1163:
	s_cmp_gt_i32 s31, 11
	s_cselect_b64 s[0:1], -1, 0
	s_and_b64 s[4:5], s[6:7], s[0:1]
	s_andn2_b64 vcc, exec, s[4:5]
	s_cbranch_vccnz .LBB0_1213
	s_waitcnt vmcnt(0)
	s_barrier
	v_cmp_eq_u32_e32 vcc, 0, v195
	s_and_saveexec_b64 s[4:5], vcc
	s_cbranch_execz .Ltb1213_done
	s_and_b32 s3, s2, 7
	s_lshl_b32 s3, s3, 3
	s_bfe_u32 s13, s2, 0x30003
	s_or_b32 s3, s3, s13
	s_lshl_b32 s3, s3, 5
	s_add_u32 s8, s28, 0x3903600
	s_addc_u32 s9, s29, 0
	v_mov_b32_e32 v0, s3
	v_mov_b32_e32 v1, 1
	v_mov_b32_e32 v2, 40
	s_mov_b32 s15, 0
	s_cmp_eq_u32 s99, 1
	s_cbranch_scc1 .Ltb1213_fast
	buffer_wbl2 sc1
	s_waitcnt vmcnt(0)
	global_atomic_add v0, v1, s[8:9]

; __device__ __forceinline__ unsigned xb_add(unsigned* p, unsigned v) { return __hip_atomic_fetch_add(p, v, __ATOMIC_RELAXED, __HIP_MEMORY_SCOPE_AGENT); }
; #define SEAM(k) do { if (IN(k) && IN((k) + 1)) { xcd_barrier(xbar); } } while (0)
; __device__ __forceinline__ void xcd_barrier(const XcdBarrier& b) {
;     asm volatile("s_waitcnt vmcnt(0)" ::: "memory");
;     __syncthreads();
;     if (threadIdx.x == 0) {
;         unsigned* bar = b.bar;
;         __builtin_amdgcn_s_waitcnt(0);
;         unsigned nloc = b.st[0], nx = b.st[1];
;         if (nloc == 0u) { xcd_barrier_complete(bar, b.x, nloc, nx); b.st[0] = nloc; b.st[1] = nx; }
;         const unsigned old = xb_add(&bar[XB_XSUB(b.x)], 1u);
;         const unsigned gen = old / nloc;
;         if (old + 1u == (gen + 1u) * nloc) {
;             __builtin_amdgcn_fence(__ATOMIC_RELEASE, "agent");
;             asm volatile("s_waitcnt vmcnt(0)" ::: "memory");
;             const unsigned og = xb_add(&bar[XB_TOP], 1u);
; __global__ void __launch_bounds__(NWAVES * 64, 2) mk_fwd(Args a) {
;     ...
;     SEAM(11);
.LBB0_1259:
	s_cmp_gt_i32 s31, 12
	s_cselect_b64 s[0:1], -1, 0
	s_and_b64 s[4:5], s[8:9], s[0:1]
	s_andn2_b64 vcc, exec, s[4:5]
	s_cbranch_vccnz .LBB0_1309
	s_waitcnt vmcnt(0)
	s_barrier
	v_cmp_eq_u32_e32 vcc, 0, v195
	s_and_saveexec_b64 s[4:5], vcc
	s_cbranch_execz .Ltb1309_done
	s_and_b32 s3, s2, 7
	s_lshl_b32 s3, s3, 3
	s_bfe_u32 s13, s2, 0x30003
	s_or_b32 s3, s3, s13
	s_lshl_b32 s3, s3, 5
	s_add_u32 s8, s28, 0x3903600
	s_addc_u32 s9, s29, 0
	v_mov_b32_e32 v0, s3
	v_mov_b32_e32 v1, 1
	v_mov_b32_e32 v2, 44
	s_mov_b32 s15, 0
	s_cmp_eq_u32 s99, 1
	s_cbranch_scc1 .Ltb1309_fast
	buffer_wbl2 sc1
	s_waitcnt vmcnt(0)
	global_atomic_add v0, v1, s[8:9]

; __device__ __forceinline__ unsigned xb_add(unsigned* p, unsigned v) { return __hip_atomic_fetch_add(p, v, __ATOMIC_RELAXED, __HIP_MEMORY_SCOPE_AGENT); }
; #define SEAM(k) do { if (IN(k) && IN((k) + 1)) { xcd_barrier(xbar); } } while (0)
; __device__ __forceinline__ void xcd_barrier(const XcdBarrier& b) {
;     asm volatile("s_waitcnt vmcnt(0)" ::: "memory");
;     __syncthreads();
;     if (threadIdx.x == 0) {
;         unsigned* bar = b.bar;
;         __builtin_amdgcn_s_waitcnt(0);
;         unsigned nloc = b.st[0], nx = b.st[1];
;         if (nloc == 0u) { xcd_barrier_complete(bar, b.x, nloc, nx); b.st[0] = nloc; b.st[1] = nx; }
;         const unsigned old = xb_add(&bar[XB_XSUB(b.x)], 1u);
;         const unsigned gen = old / nloc;
;         if (old + 1u == (gen + 1u) * nloc) {
;             __builtin_amdgcn_fence(__ATOMIC_RELEASE, "agent");
;             asm volatile("s_waitcnt vmcnt(0)" ::: "memory");
;             const unsigned og = xb_add(&bar[XB_TOP], 1u);
; __global__ void __launch_bounds__(NWAVES * 64, 2) mk_fwd(Args a) {
;     ...
;     SEAM(13);
.LBB0_1396:
	s_cmp_gt_i32 s31, 14
	s_cselect_b64 s[0:1], -1, 0
	s_and_b64 s[4:5], s[8:9], s[0:1]
	s_andn2_b64 vcc, exec, s[4:5]
	s_cbranch_vccnz .LBB0_1446
	s_waitcnt vmcnt(0)
	s_barrier
	v_cmp_eq_u32_e32 vcc, 0, v195
	s_and_saveexec_b64 s[4:5], vcc
	s_cbranch_execz .Ltb1446_done
	s_and_b32 s3, s2, 7
	s_lshl_b32 s3, s3, 3
	s_bfe_u32 s13, s2, 0x30003
	s_or_b32 s3, s3, s13
	s_lshl_b32 s3, s3, 5
	s_add_u32 s8, s28, 0x3903600
	s_addc_u32 s9, s29, 0
	v_mov_b32_e32 v0, s3
	v_mov_b32_e32 v1, 1
	v_mov_b32_e32 v2, 48
	s_mov_b32 s15, 0
	s_cmp_eq_u32 s99, 1
	s_cbranch_scc1 .Ltb1446_fast
	buffer_wbl2 sc1
	s_waitcnt vmcnt(0)
	global_atomic_add v0, v1, s[8:9]
